# v75 + nt (streaming) policy on the epilogue stores of the four widest GEMM outputs (in-proj Y/Y1 and swiglu HID), which are not re-read until the next phase
# speedup vs baseline: 1.0048x; 1.0048x over previous
; __device__ __forceinline__ unsigned cvt_pk_bf16(float lo, float hi) { unsigned r; asm volatile("v_cvt_pk_bf16_f32 %0, %1, %2" : "=v"(r) : "v"(lo), "v"(hi)); return r; }
;     __device__ __forceinline__ void operator()(const f32x4 (&acc)[2][2][4][2], const Unit& u, int wr, int wc, int fr, int fq) const {
;     ...
;             for (int m = 0; m < 4; ++m) { const int r = row0 + ai * HALF + m * 16;
; #pragma unroll
;                 for (int bj = 0; bj < 2; ++bj) { const f32x4 v0 = acc[ai][bj][m][0], v1 = acc[ai][bj][m][1]; const int col = col0 + bj * HALF;
;                     u32x4 w; w.x = cvt_pk_bf16(v0[0], v0[1]); w.y = cvt_pk_bf16(v0[2], v0[3]); w.z = cvt_pk_bf16(v1[0], v1[1]); w.w = cvt_pk_bf16(v1[2], v1[3]);
;                     bf16_t* dst = (u.pn < 4) ? (UG + ((size_t)(col >> 4) * SEQ + r) * 16 + (col & 15)) : (O + (size_t)r * ldc + col);
;                     *(u32x4*)dst = w; } }
.LBB0_266:
	global_store_dwordx4 v[154:155], v[124:127], off nt
	v_cvt_pk_bf16_f32 v116, v116, v117
	v_cvt_pk_bf16_f32 v117, v118, v119
	v_cvt_pk_bf16_f32 v118, v112, v113
	v_cndmask_b32_e64 v112, 0, 1, s[28:29]
	v_cmp_ne_u32_e64 s[4:5], 1, v112
	s_andn2_b64 vcc, exec, s[28:29]
	s_mov_b64 s[28:29], -1
	v_cvt_pk_bf16_f32 v119, v114, v115
	s_cbranch_vccnz .LBB0_268
	v_mov_b32_e32 v149, v137
	v_lshl_add_u64 v[112:113], v[148:149], 1, v[152:153]
	v_lshl_add_u64 v[114:115], v[112:113], 0, s[18:19]
	s_mov_b64 s[28:29], 0

; __device__ __forceinline__ unsigned cvt_pk_bf16(float lo, float hi) { unsigned r; asm volatile("v_cvt_pk_bf16_f32 %0, %1, %2" : "=v"(r) : "v"(lo), "v"(hi)); return r; }
;     __device__ __forceinline__ void operator()(const f32x4 (&acc)[2][2][4][2], const Unit& u, int wr, int wc, int fr, int fq) const {
;     ...
;                 for (int bj = 0; bj < 2; ++bj) { const f32x4 v0 = acc[ai][bj][m][0], v1 = acc[ai][bj][m][1]; const int col = col0 + bj * HALF;
;                     u32x4 w; w.x = cvt_pk_bf16(v0[0], v0[1]); w.y = cvt_pk_bf16(v0[2], v0[3]); w.z = cvt_pk_bf16(v1[0], v1[1]); w.w = cvt_pk_bf16(v1[2], v1[3]);
;                     bf16_t* dst = (u.pn < 4) ? (UG + ((size_t)(col >> 4) * SEQ + r) * 16 + (col & 15)) : (O + (size_t)r * ldc + col);
;                     *(u32x4*)dst = w; } }
.LBB0_270:
	global_store_dwordx4 v[114:115], v[116:119], off nt
	v_or_b32_e32 v114, 16, v150
	v_ashrrev_i32_e32 v115, 31, v114
	v_cvt_pk_bf16_f32 v108, v108, v109
	v_cvt_pk_bf16_f32 v109, v110, v111
	v_cvt_pk_bf16_f32 v110, v104, v105
	v_lshlrev_b64 v[104:105], 13, v[114:115]
	v_cvt_pk_bf16_f32 v111, v106, v107
	s_mov_b64 s[28:29], -1
	s_and_b64 vcc, exec, s[4:5]
	v_lshl_add_u64 v[106:107], s[10:11], 0, v[104:105]
	s_cbranch_vccnz .LBB0_272
	v_mov_b32_e32 v149, v137
	v_lshl_add_u64 v[116:117], v[148:149], 1, v[106:107]
	s_mov_b64 s[28:29], 0

; __device__ __forceinline__ unsigned cvt_pk_bf16(float lo, float hi) { unsigned r; asm volatile("v_cvt_pk_bf16_f32 %0, %1, %2" : "=v"(r) : "v"(lo), "v"(hi)); return r; }
;     __device__ __forceinline__ void operator()(const f32x4 (&acc)[2][2][4][2], const Unit& u, int wr, int wc, int fr, int fq) const {
;     ...
;                 for (int bj = 0; bj < 2; ++bj) { const f32x4 v0 = acc[ai][bj][m][0], v1 = acc[ai][bj][m][1]; const int col = col0 + bj * HALF;
;                     u32x4 w; w.x = cvt_pk_bf16(v0[0], v0[1]); w.y = cvt_pk_bf16(v0[2], v0[3]); w.z = cvt_pk_bf16(v1[0], v1[1]); w.w = cvt_pk_bf16(v1[2], v1[3]);
;                     bf16_t* dst = (u.pn < 4) ? (UG + ((size_t)(col >> 4) * SEQ + r) * 16 + (col & 15)) : (O + (size_t)r * ldc + col);
;                     *(u32x4*)dst = w; } }
.LBB0_274:
	s_and_b64 vcc, exec, s[4:5]
	s_mov_b64 s[28:29], -1
	global_store_dwordx4 v[116:117], v[108:111], off nt
	v_cvt_pk_bf16_f32 v100, v100, v101
	v_cvt_pk_bf16_f32 v101, v102, v103
	v_cvt_pk_bf16_f32 v102, v96, v97
	v_cvt_pk_bf16_f32 v103, v98, v99
	s_cbranch_vccnz .LBB0_276
	v_mov_b32_e32 v149, v137
	v_lshl_add_u64 v[96:97], v[148:149], 1, v[106:107]
	v_lshl_add_u64 v[96:97], v[96:97], 0, s[18:19]
	s_mov_b64 s[28:29], 0

; __device__ __forceinline__ unsigned cvt_pk_bf16(float lo, float hi) { unsigned r; asm volatile("v_cvt_pk_bf16_f32 %0, %1, %2" : "=v"(r) : "v"(lo), "v"(hi)); return r; }
;     __device__ __forceinline__ void operator()(const f32x4 (&acc)[2][2][4][2], const Unit& u, int wr, int wc, int fr, int fq) const {
;     ...
;                 for (int bj = 0; bj < 2; ++bj) { const f32x4 v0 = acc[ai][bj][m][0], v1 = acc[ai][bj][m][1]; const int col = col0 + bj * HALF;
;                     u32x4 w; w.x = cvt_pk_bf16(v0[0], v0[1]); w.y = cvt_pk_bf16(v0[2], v0[3]); w.z = cvt_pk_bf16(v1[0], v1[1]); w.w = cvt_pk_bf16(v1[2], v1[3]);
;                     bf16_t* dst = (u.pn < 4) ? (UG + ((size_t)(col >> 4) * SEQ + r) * 16 + (col & 15)) : (O + (size_t)r * ldc + col);
;                     *(u32x4*)dst = w; } }
.LBB0_278:
	global_store_dwordx4 v[96:97], v[100:103], off nt
	v_or_b32_e32 v96, 32, v150
	v_ashrrev_i32_e32 v97, 31, v96
	v_cvt_pk_bf16_f32 v92, v92, v93
	v_cvt_pk_bf16_f32 v93, v94, v95
	v_cvt_pk_bf16_f32 v94, v88, v89
	v_lshlrev_b64 v[88:89], 13, v[96:97]
	v_cvt_pk_bf16_f32 v95, v90, v91
	s_mov_b64 s[28:29], -1
	s_and_b64 vcc, exec, s[4:5]
	v_lshl_add_u64 v[90:91], s[10:11], 0, v[88:89]
	s_cbranch_vccnz .LBB0_280
	v_mov_b32_e32 v149, v137
	v_lshl_add_u64 v[98:99], v[148:149], 1, v[90:91]
	s_mov_b64 s[28:29], 0

; __device__ __forceinline__ unsigned cvt_pk_bf16(float lo, float hi) { unsigned r; asm volatile("v_cvt_pk_bf16_f32 %0, %1, %2" : "=v"(r) : "v"(lo), "v"(hi)); return r; }
;     __device__ __forceinline__ void operator()(const f32x4 (&acc)[2][2][4][2], const Unit& u, int wr, int wc, int fr, int fq) const {
;     ...
;                 for (int bj = 0; bj < 2; ++bj) { const f32x4 v0 = acc[ai][bj][m][0], v1 = acc[ai][bj][m][1]; const int col = col0 + bj * HALF;
;                     u32x4 w; w.x = cvt_pk_bf16(v0[0], v0[1]); w.y = cvt_pk_bf16(v0[2], v0[3]); w.z = cvt_pk_bf16(v1[0], v1[1]); w.w = cvt_pk_bf16(v1[2], v1[3]);
;                     bf16_t* dst = (u.pn < 4) ? (UG + ((size_t)(col >> 4) * SEQ + r) * 16 + (col & 15)) : (O + (size_t)r * ldc + col);
;                     *(u32x4*)dst = w; } }
.LBB0_282:
	s_and_b64 vcc, exec, s[4:5]
	s_mov_b64 s[28:29], -1
	global_store_dwordx4 v[98:99], v[92:95], off nt
	v_cvt_pk_bf16_f32 v84, v84, v85
	v_cvt_pk_bf16_f32 v85, v86, v87
	v_cvt_pk_bf16_f32 v86, v80, v81
	v_cvt_pk_bf16_f32 v87, v82, v83
	s_cbranch_vccnz .LBB0_284
	v_mov_b32_e32 v149, v137
	v_lshl_add_u64 v[80:81], v[148:149], 1, v[90:91]
	v_lshl_add_u64 v[80:81], v[80:81], 0, s[18:19]
	s_mov_b64 s[28:29], 0

; __device__ __forceinline__ unsigned cvt_pk_bf16(float lo, float hi) { unsigned r; asm volatile("v_cvt_pk_bf16_f32 %0, %1, %2" : "=v"(r) : "v"(lo), "v"(hi)); return r; }
;     __device__ __forceinline__ void operator()(const f32x4 (&acc)[2][2][4][2], const Unit& u, int wr, int wc, int fr, int fq) const {
;     ...
;                 for (int bj = 0; bj < 2; ++bj) { const f32x4 v0 = acc[ai][bj][m][0], v1 = acc[ai][bj][m][1]; const int col = col0 + bj * HALF;
;                     u32x4 w; w.x = cvt_pk_bf16(v0[0], v0[1]); w.y = cvt_pk_bf16(v0[2], v0[3]); w.z = cvt_pk_bf16(v1[0], v1[1]); w.w = cvt_pk_bf16(v1[2], v1[3]);
;                     bf16_t* dst = (u.pn < 4) ? (UG + ((size_t)(col >> 4) * SEQ + r) * 16 + (col & 15)) : (O + (size_t)r * ldc + col);
;                     *(u32x4*)dst = w; } }
.LBB0_286:
	global_store_dwordx4 v[80:81], v[84:87], off nt
	v_or_b32_e32 v80, 48, v150
	v_ashrrev_i32_e32 v81, 31, v80
	v_cvt_pk_bf16_f32 v76, v76, v77
	v_cvt_pk_bf16_f32 v77, v78, v79
	v_cvt_pk_bf16_f32 v78, v72, v73
	v_lshlrev_b64 v[72:73], 13, v[80:81]
	v_cvt_pk_bf16_f32 v79, v74, v75
	s_mov_b64 s[28:29], -1
	s_and_b64 vcc, exec, s[4:5]
	v_lshl_add_u64 v[74:75], s[10:11], 0, v[72:73]
	s_cbranch_vccnz .LBB0_288
	v_mov_b32_e32 v149, v137
	v_lshl_add_u64 v[82:83], v[148:149], 1, v[74:75]
	s_mov_b64 s[28:29], 0

; __device__ __forceinline__ unsigned cvt_pk_bf16(float lo, float hi) { unsigned r; asm volatile("v_cvt_pk_bf16_f32 %0, %1, %2" : "=v"(r) : "v"(lo), "v"(hi)); return r; }
;     __device__ __forceinline__ void operator()(const f32x4 (&acc)[2][2][4][2], const Unit& u, int wr, int wc, int fr, int fq) const {
;     ...
;                 for (int bj = 0; bj < 2; ++bj) { const f32x4 v0 = acc[ai][bj][m][0], v1 = acc[ai][bj][m][1]; const int col = col0 + bj * HALF;
;                     u32x4 w; w.x = cvt_pk_bf16(v0[0], v0[1]); w.y = cvt_pk_bf16(v0[2], v0[3]); w.z = cvt_pk_bf16(v1[0], v1[1]); w.w = cvt_pk_bf16(v1[2], v1[3]);
;                     bf16_t* dst = (u.pn < 4) ? (UG + ((size_t)(col >> 4) * SEQ + r) * 16 + (col & 15)) : (O + (size_t)r * ldc + col);
;                     *(u32x4*)dst = w; } }
.LBB0_290:
	s_and_b64 vcc, exec, s[4:5]
	s_mov_b64 s[28:29], -1
	global_store_dwordx4 v[82:83], v[76:79], off nt
	v_cvt_pk_bf16_f32 v68, v68, v69
	v_cvt_pk_bf16_f32 v69, v70, v71
	v_cvt_pk_bf16_f32 v70, v64, v65
	v_cvt_pk_bf16_f32 v71, v66, v67
	s_cbranch_vccnz .LBB0_292
	v_mov_b32_e32 v149, v137
	v_lshl_add_u64 v[64:65], v[148:149], 1, v[74:75]
	v_lshl_add_u64 v[64:65], v[64:65], 0, s[18:19]
	s_mov_b64 s[28:29], 0

; __device__ __forceinline__ unsigned cvt_pk_bf16(float lo, float hi) { unsigned r; asm volatile("v_cvt_pk_bf16_f32 %0, %1, %2" : "=v"(r) : "v"(lo), "v"(hi)); return r; }
;     __device__ __forceinline__ void operator()(const f32x4 (&acc)[2][2][4][2], const Unit& u, int wr, int wc, int fr, int fq) const {
;     ...
;                 for (int bj = 0; bj < 2; ++bj) { const f32x4 v0 = acc[ai][bj][m][0], v1 = acc[ai][bj][m][1]; const int col = col0 + bj * HALF;
;                     u32x4 w; w.x = cvt_pk_bf16(v0[0], v0[1]); w.y = cvt_pk_bf16(v0[2], v0[3]); w.z = cvt_pk_bf16(v1[0], v1[1]); w.w = cvt_pk_bf16(v1[2], v1[3]);
;                     bf16_t* dst = (u.pn < 4) ? (UG + ((size_t)(col >> 4) * SEQ + r) * 16 + (col & 15)) : (O + (size_t)r * ldc + col);
;                     *(u32x4*)dst = w; } }
.LBB0_294:
	global_store_dwordx4 v[64:65], v[68:71], off nt
	v_add_u32_e32 v64, 0x80, v150
	v_ashrrev_i32_e32 v65, 31, v64
	v_cvt_pk_bf16_f32 v60, v60, v61
	v_cvt_pk_bf16_f32 v61, v62, v63
	v_cvt_pk_bf16_f32 v62, v56, v57
	v_lshlrev_b64 v[56:57], 13, v[64:65]
	v_cvt_pk_bf16_f32 v63, v58, v59
	s_mov_b64 s[28:29], -1
	s_and_b64 vcc, exec, s[4:5]
	v_lshl_add_u64 v[58:59], s[10:11], 0, v[56:57]
	s_cbranch_vccnz .LBB0_296
	v_mov_b32_e32 v149, v137
	v_lshl_add_u64 v[66:67], v[148:149], 1, v[58:59]
	s_mov_b64 s[28:29], 0

; __device__ __forceinline__ unsigned cvt_pk_bf16(float lo, float hi) { unsigned r; asm volatile("v_cvt_pk_bf16_f32 %0, %1, %2" : "=v"(r) : "v"(lo), "v"(hi)); return r; }
;     __device__ __forceinline__ void operator()(const f32x4 (&acc)[2][2][4][2], const Unit& u, int wr, int wc, int fr, int fq) const {
;     ...
;                 for (int bj = 0; bj < 2; ++bj) { const f32x4 v0 = acc[ai][bj][m][0], v1 = acc[ai][bj][m][1]; const int col = col0 + bj * HALF;
;                     u32x4 w; w.x = cvt_pk_bf16(v0[0], v0[1]); w.y = cvt_pk_bf16(v0[2], v0[3]); w.z = cvt_pk_bf16(v1[0], v1[1]); w.w = cvt_pk_bf16(v1[2], v1[3]);
;                     bf16_t* dst = (u.pn < 4) ? (UG + ((size_t)(col >> 4) * SEQ + r) * 16 + (col & 15)) : (O + (size_t)r * ldc + col);
;                     *(u32x4*)dst = w; } }
.LBB0_298:
	s_and_b64 vcc, exec, s[4:5]
	s_mov_b64 s[28:29], -1
	global_store_dwordx4 v[66:67], v[60:63], off nt
	v_cvt_pk_bf16_f32 v52, v52, v53
	v_cvt_pk_bf16_f32 v53, v54, v55
	v_cvt_pk_bf16_f32 v54, v48, v49
	v_cvt_pk_bf16_f32 v55, v50, v51
	s_cbranch_vccnz .LBB0_300
	v_mov_b32_e32 v149, v137
	v_lshl_add_u64 v[48:49], v[148:149], 1, v[58:59]
	v_lshl_add_u64 v[48:49], v[48:49], 0, s[18:19]
	s_mov_b64 s[28:29], 0

; __device__ __forceinline__ unsigned cvt_pk_bf16(float lo, float hi) { unsigned r; asm volatile("v_cvt_pk_bf16_f32 %0, %1, %2" : "=v"(r) : "v"(lo), "v"(hi)); return r; }
;     __device__ __forceinline__ void operator()(const f32x4 (&acc)[2][2][4][2], const Unit& u, int wr, int wc, int fr, int fq) const {
;     ...
;                 for (int bj = 0; bj < 2; ++bj) { const f32x4 v0 = acc[ai][bj][m][0], v1 = acc[ai][bj][m][1]; const int col = col0 + bj * HALF;
;                     u32x4 w; w.x = cvt_pk_bf16(v0[0], v0[1]); w.y = cvt_pk_bf16(v0[2], v0[3]); w.z = cvt_pk_bf16(v1[0], v1[1]); w.w = cvt_pk_bf16(v1[2], v1[3]);
;                     bf16_t* dst = (u.pn < 4) ? (UG + ((size_t)(col >> 4) * SEQ + r) * 16 + (col & 15)) : (O + (size_t)r * ldc + col);
;                     *(u32x4*)dst = w; } }
.LBB0_302:
	global_store_dwordx4 v[48:49], v[52:55], off nt
	v_add_u32_e32 v48, 0x90, v150
	v_ashrrev_i32_e32 v49, 31, v48
	v_cvt_pk_bf16_f32 v44, v44, v45
	v_cvt_pk_bf16_f32 v45, v46, v47
	v_cvt_pk_bf16_f32 v46, v40, v41
	v_lshlrev_b64 v[40:41], 13, v[48:49]
	v_cvt_pk_bf16_f32 v47, v42, v43
	s_mov_b64 s[28:29], -1
	s_and_b64 vcc, exec, s[4:5]
	v_lshl_add_u64 v[42:43], s[10:11], 0, v[40:41]
	s_cbranch_vccnz .LBB0_304
	v_mov_b32_e32 v149, v137
	v_lshl_add_u64 v[50:51], v[148:149], 1, v[42:43]
	s_mov_b64 s[28:29], 0

; __device__ __forceinline__ unsigned cvt_pk_bf16(float lo, float hi) { unsigned r; asm volatile("v_cvt_pk_bf16_f32 %0, %1, %2" : "=v"(r) : "v"(lo), "v"(hi)); return r; }
;     __device__ __forceinline__ void operator()(const f32x4 (&acc)[2][2][4][2], const Unit& u, int wr, int wc, int fr, int fq) const {
;     ...
;                 for (int bj = 0; bj < 2; ++bj) { const f32x4 v0 = acc[ai][bj][m][0], v1 = acc[ai][bj][m][1]; const int col = col0 + bj * HALF;
;                     u32x4 w; w.x = cvt_pk_bf16(v0[0], v0[1]); w.y = cvt_pk_bf16(v0[2], v0[3]); w.z = cvt_pk_bf16(v1[0], v1[1]); w.w = cvt_pk_bf16(v1[2], v1[3]);
;                     bf16_t* dst = (u.pn < 4) ? (UG + ((size_t)(col >> 4) * SEQ + r) * 16 + (col & 15)) : (O + (size_t)r * ldc + col);
;                     *(u32x4*)dst = w; } }
.LBB0_306:
	s_and_b64 vcc, exec, s[4:5]
	s_mov_b64 s[28:29], -1
	global_store_dwordx4 v[50:51], v[44:47], off nt
	v_cvt_pk_bf16_f32 v36, v36, v37
	v_cvt_pk_bf16_f32 v37, v38, v39
	v_cvt_pk_bf16_f32 v38, v32, v33
	v_cvt_pk_bf16_f32 v39, v34, v35
	s_cbranch_vccnz .LBB0_308
	v_mov_b32_e32 v149, v137
	v_lshl_add_u64 v[32:33], v[148:149], 1, v[42:43]
	v_lshl_add_u64 v[32:33], v[32:33], 0, s[18:19]
	s_mov_b64 s[28:29], 0

; __device__ __forceinline__ unsigned cvt_pk_bf16(float lo, float hi) { unsigned r; asm volatile("v_cvt_pk_bf16_f32 %0, %1, %2" : "=v"(r) : "v"(lo), "v"(hi)); return r; }
;     __device__ __forceinline__ void operator()(const f32x4 (&acc)[2][2][4][2], const Unit& u, int wr, int wc, int fr, int fq) const {
;     ...
;                 for (int bj = 0; bj < 2; ++bj) { const f32x4 v0 = acc[ai][bj][m][0], v1 = acc[ai][bj][m][1]; const int col = col0 + bj * HALF;
;                     u32x4 w; w.x = cvt_pk_bf16(v0[0], v0[1]); w.y = cvt_pk_bf16(v0[2], v0[3]); w.z = cvt_pk_bf16(v1[0], v1[1]); w.w = cvt_pk_bf16(v1[2], v1[3]);
;                     bf16_t* dst = (u.pn < 4) ? (UG + ((size_t)(col >> 4) * SEQ + r) * 16 + (col & 15)) : (O + (size_t)r * ldc + col);
;                     *(u32x4*)dst = w; } }
.LBB0_310:
	global_store_dwordx4 v[32:33], v[36:39], off nt
	v_add_u32_e32 v32, 0xa0, v150
	v_ashrrev_i32_e32 v33, 31, v32
	v_cvt_pk_bf16_f32 v28, v28, v29
	v_cvt_pk_bf16_f32 v29, v30, v31
	v_cvt_pk_bf16_f32 v30, v24, v25
	v_lshlrev_b64 v[24:25], 13, v[32:33]
	v_cvt_pk_bf16_f32 v31, v26, v27
	s_mov_b64 s[28:29], -1
	s_and_b64 vcc, exec, s[4:5]
	v_lshl_add_u64 v[26:27], s[10:11], 0, v[24:25]
	s_cbranch_vccnz .LBB0_312
	v_mov_b32_e32 v149, v137
	v_lshl_add_u64 v[34:35], v[148:149], 1, v[26:27]
	s_mov_b64 s[28:29], 0

; __device__ __forceinline__ unsigned cvt_pk_bf16(float lo, float hi) { unsigned r; asm volatile("v_cvt_pk_bf16_f32 %0, %1, %2" : "=v"(r) : "v"(lo), "v"(hi)); return r; }
;     __device__ __forceinline__ void operator()(const f32x4 (&acc)[2][2][4][2], const Unit& u, int wr, int wc, int fr, int fq) const {
;     ...
;                 for (int bj = 0; bj < 2; ++bj) { const f32x4 v0 = acc[ai][bj][m][0], v1 = acc[ai][bj][m][1]; const int col = col0 + bj * HALF;
;                     u32x4 w; w.x = cvt_pk_bf16(v0[0], v0[1]); w.y = cvt_pk_bf16(v0[2], v0[3]); w.z = cvt_pk_bf16(v1[0], v1[1]); w.w = cvt_pk_bf16(v1[2], v1[3]);
;                     bf16_t* dst = (u.pn < 4) ? (UG + ((size_t)(col >> 4) * SEQ + r) * 16 + (col & 15)) : (O + (size_t)r * ldc + col);
;                     *(u32x4*)dst = w; } }
.LBB0_314:
	s_and_b64 vcc, exec, s[4:5]
	s_mov_b64 s[28:29], -1
	global_store_dwordx4 v[34:35], v[28:31], off nt
	v_cvt_pk_bf16_f32 v20, v20, v21
	v_cvt_pk_bf16_f32 v21, v22, v23
	v_cvt_pk_bf16_f32 v22, v16, v17
	v_cvt_pk_bf16_f32 v23, v18, v19
	s_cbranch_vccnz .LBB0_316
	v_mov_b32_e32 v149, v137
	v_lshl_add_u64 v[16:17], v[148:149], 1, v[26:27]
	v_lshl_add_u64 v[16:17], v[16:17], 0, s[18:19]
	s_mov_b64 s[28:29], 0

; __device__ __forceinline__ unsigned cvt_pk_bf16(float lo, float hi) { unsigned r; asm volatile("v_cvt_pk_bf16_f32 %0, %1, %2" : "=v"(r) : "v"(lo), "v"(hi)); return r; }
;     __device__ __forceinline__ void operator()(const f32x4 (&acc)[2][2][4][2], const Unit& u, int wr, int wc, int fr, int fq) const {
;     ...
;                 for (int bj = 0; bj < 2; ++bj) { const f32x4 v0 = acc[ai][bj][m][0], v1 = acc[ai][bj][m][1]; const int col = col0 + bj * HALF;
;                     u32x4 w; w.x = cvt_pk_bf16(v0[0], v0[1]); w.y = cvt_pk_bf16(v0[2], v0[3]); w.z = cvt_pk_bf16(v1[0], v1[1]); w.w = cvt_pk_bf16(v1[2], v1[3]);
;                     bf16_t* dst = (u.pn < 4) ? (UG + ((size_t)(col >> 4) * SEQ + r) * 16 + (col & 15)) : (O + (size_t)r * ldc + col);
;                     *(u32x4*)dst = w; } }
.LBB0_318:
	global_store_dwordx4 v[16:17], v[20:23], off nt
	v_add_u32_e32 v16, 0xb0, v150
	v_ashrrev_i32_e32 v17, 31, v16
	v_cvt_pk_bf16_f32 v12, v12, v13
	v_cvt_pk_bf16_f32 v13, v14, v15
	v_cvt_pk_bf16_f32 v14, v8, v9
	v_lshlrev_b64 v[8:9], 13, v[16:17]
	v_cvt_pk_bf16_f32 v15, v10, v11
	s_mov_b64 s[28:29], -1
	s_and_b64 vcc, exec, s[4:5]
	v_lshl_add_u64 v[10:11], s[10:11], 0, v[8:9]
	s_cbranch_vccnz .LBB0_320
	v_mov_b32_e32 v149, v137
	v_lshl_add_u64 v[18:19], v[148:149], 1, v[10:11]
	s_mov_b64 s[28:29], 0

; __device__ __forceinline__ unsigned cvt_pk_bf16(float lo, float hi) { unsigned r; asm volatile("v_cvt_pk_bf16_f32 %0, %1, %2" : "=v"(r) : "v"(lo), "v"(hi)); return r; }
;     __device__ __forceinline__ void operator()(const f32x4 (&acc)[2][2][4][2], const Unit& u, int wr, int wc, int fr, int fq) const {
;     ...
;                 for (int bj = 0; bj < 2; ++bj) { const f32x4 v0 = acc[ai][bj][m][0], v1 = acc[ai][bj][m][1]; const int col = col0 + bj * HALF;
;                     u32x4 w; w.x = cvt_pk_bf16(v0[0], v0[1]); w.y = cvt_pk_bf16(v0[2], v0[3]); w.z = cvt_pk_bf16(v1[0], v1[1]); w.w = cvt_pk_bf16(v1[2], v1[3]);
;                     bf16_t* dst = (u.pn < 4) ? (UG + ((size_t)(col >> 4) * SEQ + r) * 16 + (col & 15)) : (O + (size_t)r * ldc + col);
;                     *(u32x4*)dst = w; } }
.LBB0_322:
	s_and_b64 vcc, exec, s[4:5]
	s_mov_b64 s[4:5], -1
	global_store_dwordx4 v[18:19], v[12:15], off nt
	v_cvt_pk_bf16_f32 v4, v4, v5
	v_cvt_pk_bf16_f32 v5, v6, v7
	v_cvt_pk_bf16_f32 v6, v0, v1
	v_cvt_pk_bf16_f32 v7, v2, v3
	s_cbranch_vccz .LBB0_325
	s_andn2_b64 vcc, exec, s[4:5]
	s_cbranch_vccz .LBB0_326
.LBB0_324:
	s_andn2_b64 vcc, exec, s[0:1]
	s_mov_b64 s[0:1], -1
	global_store_dwordx4 v[0:1], v[4:7], off nt
	s_cbranch_vccnz .LBB0_251
	s_branch .LBB0_327

; __device__ __forceinline__ unsigned cvt_pk_bf16(float lo, float hi) { unsigned r; asm volatile("v_cvt_pk_bf16_f32 %0, %1, %2" : "=v"(r) : "v"(lo), "v"(hi)); return r; }
;     __device__ __forceinline__ void operator()(const f32x4 (&acc)[2][2][4][2], const Unit& u, int wr, int wc, int fr, int fq) const {
;     ...
;                 for (int bj = 0; bj < 2; ++bj) { const f32x4 v0 = acc[ai][bj][m][0], v1 = acc[ai][bj][m][1]; const int col = col0 + bj * HALF;
;                     u32x4 w; w.x = cvt_pk_bf16(v0[0], v0[1]); w.y = cvt_pk_bf16(v0[2], v0[3]); w.z = cvt_pk_bf16(v1[0], v1[1]); w.w = cvt_pk_bf16(v1[2], v1[3]);
;                     bf16_t* dst = (u.pn < 4) ? (UG + ((size_t)(col >> 4) * SEQ + r) * 16 + (col & 15)) : (O + (size_t)r * ldc + col);
;                     *(u32x4*)dst = w; } }
.LBB0_326:
	v_lshlrev_b64 v[0:1], 19, v[112:113]
	v_lshl_add_u64 v[0:1], s[12:13], 0, v[0:1]
	v_lshl_add_u64 v[0:1], v[0:1], 0, v[8:9]
	v_lshl_add_u64 v[0:1], v[0:1], 0, v[136:137]
	s_andn2_b64 vcc, exec, s[0:1]
	s_mov_b64 s[0:1], -1
	global_store_dwordx4 v[0:1], v[4:7], off nt
	s_cbranch_vccnz .LBB0_251

; __device__ __forceinline__ unsigned cvt_pk_bf16(float lo, float hi) { unsigned r; asm volatile("v_cvt_pk_bf16_f32 %0, %1, %2" : "=v"(r) : "v"(lo), "v"(hi)); return r; }
; __device__ __forceinline__ float siluf_(float x) { return x * __builtin_amdgcn_rcpf(1.0f + __expf(-x)); }
;     __device__ __forceinline__ void operator()(const f32x4 (&acc)[2][2][4][2], const Unit& u, int wr, int wc, int fr, int fq) const {
;         const int row0 = u.pm * BM + wr * 64 + fr, col0 = u.pn * HALF + wc * 32 + 8 * fq;
; #pragma unroll
;         for (int ai = 0; ai < 2; ++ai)
; #pragma unroll
;             for (int m = 0; m < 4; ++m) { bf16_t* rowp = O + (size_t)(row0 + ai * HALF + m * 16) * ldc + col0;
;                 float o[8];
; #pragma unroll
;                 for (int n = 0; n < 2; ++n)
; #pragma unroll
;                     for (int j = 0; j < 4; ++j) { const float g = acc[ai][0][m][n][j], up = acc[ai][1][m][n][j]; o[4 * n + j] = siluf_(g) * up; }
;                 u32x4 w; w.x = cvt_pk_bf16(o[0], o[1]); w.y = cvt_pk_bf16(o[2], o[3]); w.z = cvt_pk_bf16(o[4], o[5]); w.w = cvt_pk_bf16(o[6], o[7]);
;                 *(u32x4*)rowp = w; }
.LBB0_1339:
	v_mul_f32_e32 v144, 0xbfb8aa3b, v124
	v_exp_f32_e32 v156, v144
	v_mul_f32_e32 v144, 0xbfb8aa3b, v125
	v_exp_f32_e32 v157, v144
	v_lshl_or_b32 v154, s52, 7, v149
	v_add_f32_e32 v156, 1.0, v156
	v_rcp_f32_e32 v158, v156
	v_add_f32_e32 v156, 1.0, v157
	v_rcp_f32_e32 v159, v156
	v_lshl_add_u32 v153, s22, 8, v147
	v_mul_f32_e32 v124, v124, v158
	v_mul_f32_e32 v116, v124, v116
	v_mul_f32_e32 v124, v125, v159
	v_mul_f32_e32 v125, 0xbfb8aa3b, v126
	v_exp_f32_e32 v125, v125
	v_mul_f32_e32 v158, 0xbfb8aa3b, v127
	v_exp_f32_e32 v158, v158
	v_mul_f32_e32 v117, v124, v117
	v_add_f32_e32 v124, 1.0, v125
	v_rcp_f32_e32 v124, v124
	v_add_f32_e32 v125, 1.0, v158
	v_mul_f32_e32 v158, 0xbfb8aa3b, v120
	v_rcp_f32_e32 v125, v125
	v_exp_f32_e32 v158, v158
	v_mul_f32_e32 v124, v126, v124
	v_mul_f32_e32 v124, v124, v118
	v_mul_f32_e32 v118, v127, v125
	v_add_f32_e32 v125, 1.0, v158
	v_rcp_f32_e32 v125, v125
	v_mul_f32_e32 v126, 0xbfb8aa3b, v121
	v_mul_f32_e32 v127, v118, v119
	v_exp_f32_e32 v126, v126
	v_mul_f32_e32 v118, v120, v125
	v_mul_f32_e32 v120, v118, v112
	v_mul_f32_e32 v118, 0xbfb8aa3b, v122
	v_exp_f32_e32 v118, v118
	v_mul_f32_e32 v119, 0xbfb8aa3b, v123
	v_exp_f32_e32 v119, v119
	v_add_f32_e32 v112, 1.0, v126
	v_rcp_f32_e32 v112, v112
	v_add_f32_e32 v118, 1.0, v118
	v_rcp_f32_e32 v118, v118
	v_add_f32_e32 v119, 1.0, v119
	v_rcp_f32_e32 v119, v119
	v_mul_f32_e32 v112, v121, v112
	v_mul_f32_e32 v121, v112, v113
	v_mul_f32_e32 v112, v122, v118
	v_ashrrev_i32_e32 v155, 31, v154
	v_mov_b64_e32 v[144:145], s[8:9]
	v_mul_f32_e32 v122, v112, v114
	v_mul_f32_e32 v112, v123, v119
	v_mad_i64_i32 v[156:157], s[24:25], v153, s49, v[144:145]
	v_mul_f32_e32 v123, v112, v115
	v_lshlrev_b64 v[112:113], 1, v[154:155]
	v_lshl_add_u64 v[118:119], v[156:157], 0, v[112:113]
	v_cvt_pk_bf16_f32 v114, v116, v117
	v_cvt_pk_bf16_f32 v115, v124, v127
	v_cvt_pk_bf16_f32 v116, v120, v121
	v_cvt_pk_bf16_f32 v117, v122, v123
	global_store_dwordx4 v[118:119], v[114:117], off nt
	s_andn2_b64 vcc, exec, s[0:1]
	s_mov_b64 s[0:1], -1
	v_mul_f32_e32 v114, 0xbfb8aa3b, v108
	v_exp_f32_e32 v114, v114
	v_mul_f32_e32 v115, 0xbfb8aa3b, v109
	v_exp_f32_e32 v115, v115
	v_or_b32_e32 v116, 16, v153
	v_add_f32_e32 v114, 1.0, v114
	v_rcp_f32_e32 v117, v114
	v_add_f32_e32 v114, 1.0, v115
	v_rcp_f32_e32 v118, v114
	v_mad_i64_i32 v[114:115], s[24:25], v116, s49, v[144:145]
	v_mul_f32_e32 v108, v108, v117
	v_mul_f32_e32 v108, v108, v100
	v_mul_f32_e32 v100, v109, v118
	v_mul_f32_e32 v109, 0xbfb8aa3b, v110
	v_exp_f32_e32 v109, v109
	v_mul_f32_e32 v116, 0xbfb8aa3b, v111
	v_exp_f32_e32 v116, v116
	v_mul_f32_e32 v117, v100, v101
	v_add_f32_e32 v100, 1.0, v109
	v_rcp_f32_e32 v100, v100
	v_add_f32_e32 v101, 1.0, v116
	v_mul_f32_e32 v109, 0xbfb8aa3b, v104
	v_rcp_f32_e32 v101, v101
	v_exp_f32_e32 v109, v109
	v_mul_f32_e32 v100, v110, v100
	v_mul_f32_e32 v102, v100, v102
	v_mul_f32_e32 v100, v111, v101
	v_add_f32_e32 v101, 1.0, v109
	v_rcp_f32_e32 v101, v101
	v_mul_f32_e32 v109, 0xbfb8aa3b, v105
	v_mul_f32_e32 v103, v100, v103
	v_exp_f32_e32 v109, v109
	v_mul_f32_e32 v100, v104, v101
	v_mul_f32_e32 v104, v100, v96
	v_mul_f32_e32 v100, 0xbfb8aa3b, v106
	v_exp_f32_e32 v100, v100
	v_mul_f32_e32 v101, 0xbfb8aa3b, v107
	v_exp_f32_e32 v101, v101
	v_add_f32_e32 v96, 1.0, v109
	v_rcp_f32_e32 v96, v96
	v_add_f32_e32 v100, 1.0, v100
	v_rcp_f32_e32 v100, v100
	v_add_f32_e32 v101, 1.0, v101
	v_rcp_f32_e32 v101, v101
	v_mul_f32_e32 v96, v105, v96
	v_mul_f32_e32 v105, v96, v97
	v_mul_f32_e32 v96, v106, v100
	v_mul_f32_e32 v106, v96, v98
	v_mul_f32_e32 v96, v107, v101
	v_mul_f32_e32 v99, v96, v99
	v_lshl_add_u64 v[100:101], v[114:115], 0, v[112:113]
	v_cvt_pk_bf16_f32 v96, v108, v117
	v_cvt_pk_bf16_f32 v97, v102, v103
	v_cvt_pk_bf16_f32 v98, v104, v105
	v_cvt_pk_bf16_f32 v99, v106, v99
	global_store_dwordx4 v[100:101], v[96:99], off nt
	s_nop 1
	v_mul_f32_e32 v96, 0xbfb8aa3b, v92
	v_exp_f32_e32 v96, v96
	v_mul_f32_e32 v97, 0xbfb8aa3b, v93
	v_exp_f32_e32 v97, v97
	v_or_b32_e32 v98, 32, v153
	v_add_f32_e32 v96, 1.0, v96
	v_rcp_f32_e32 v99, v96
	v_add_f32_e32 v96, 1.0, v97
	v_rcp_f32_e32 v100, v96
	v_mad_i64_i32 v[96:97], s[24:25], v98, s49, v[144:145]
	v_mul_f32_e32 v92, v92, v99
	v_mul_f32_e32 v92, v92, v84
	v_mul_f32_e32 v84, v93, v100
	v_mul_f32_e32 v93, 0xbfb8aa3b, v94
	v_exp_f32_e32 v93, v93
	v_mul_f32_e32 v98, 0xbfb8aa3b, v95
	v_exp_f32_e32 v98, v98
	v_mul_f32_e32 v99, v84, v85
	v_add_f32_e32 v84, 1.0, v93
	v_rcp_f32_e32 v84, v84
	v_add_f32_e32 v85, 1.0, v98
	v_mul_f32_e32 v93, 0xbfb8aa3b, v88
	v_rcp_f32_e32 v85, v85
	v_exp_f32_e32 v93, v93
	v_mul_f32_e32 v84, v94, v84
	v_mul_f32_e32 v86, v84, v86
	v_mul_f32_e32 v84, v95, v85
	v_add_f32_e32 v85, 1.0, v93
	v_rcp_f32_e32 v85, v85
	v_mul_f32_e32 v93, 0xbfb8aa3b, v89
	v_mul_f32_e32 v87, v84, v87
	v_exp_f32_e32 v93, v93
	v_mul_f32_e32 v84, v88, v85
	v_mul_f32_e32 v88, v84, v80
	v_mul_f32_e32 v84, 0xbfb8aa3b, v90
	v_exp_f32_e32 v84, v84
	v_mul_f32_e32 v85, 0xbfb8aa3b, v91
	v_exp_f32_e32 v85, v85
	v_add_f32_e32 v80, 1.0, v93
	v_rcp_f32_e32 v80, v80
	v_add_f32_e32 v84, 1.0, v84
	v_rcp_f32_e32 v84, v84
	v_add_f32_e32 v85, 1.0, v85
	v_rcp_f32_e32 v85, v85
	v_mul_f32_e32 v80, v89, v80
	v_mul_f32_e32 v89, v80, v81
	v_mul_f32_e32 v80, v90, v84
	v_mul_f32_e32 v90, v80, v82
	v_mul_f32_e32 v80, v91, v85
	v_mul_f32_e32 v83, v80, v83
	v_lshl_add_u64 v[84:85], v[96:97], 0, v[112:113]
	v_cvt_pk_bf16_f32 v80, v92, v99
	v_cvt_pk_bf16_f32 v81, v86, v87
	v_cvt_pk_bf16_f32 v82, v88, v89
	v_cvt_pk_bf16_f32 v83, v90, v83
	global_store_dwordx4 v[84:85], v[80:83], off nt
	s_nop 1
	v_mul_f32_e32 v80, 0xbfb8aa3b, v76
	v_exp_f32_e32 v80, v80
	v_mul_f32_e32 v81, 0xbfb8aa3b, v77
; __device__ __forceinline__ unsigned cvt_pk_bf16(float lo, float hi) { unsigned r; asm volatile("v_cvt_pk_bf16_f32 %0, %1, %2" : "=v"(r) : "v"(lo), "v"(hi)); return r; }
; __device__ __forceinline__ float siluf_(float x) { return x * __builtin_amdgcn_rcpf(1.0f + __expf(-x)); }
;     __device__ __forceinline__ void operator()(const f32x4 (&acc)[2][2][4][2], const Unit& u, int wr, int wc, int fr, int fq) const {
;         const int row0 = u.pm * BM + wr * 64 + fr, col0 = u.pn * HALF + wc * 32 + 8 * fq;
; #pragma unroll
;         for (int ai = 0; ai < 2; ++ai)
; #pragma unroll
;             for (int m = 0; m < 4; ++m) { bf16_t* rowp = O + (size_t)(row0 + ai * HALF + m * 16) * ldc + col0;
;                 float o[8];
; #pragma unroll
;                 for (int n = 0; n < 2; ++n)
; #pragma unroll
;                     for (int j = 0; j < 4; ++j) { const float g = acc[ai][0][m][n][j], up = acc[ai][1][m][n][j]; o[4 * n + j] = siluf_(g) * up; }
;                 u32x4 w; w.x = cvt_pk_bf16(o[0], o[1]); w.y = cvt_pk_bf16(o[2], o[3]); w.z = cvt_pk_bf16(o[4], o[5]); w.w = cvt_pk_bf16(o[6], o[7]);
;                 *(u32x4*)rowp = w; }
	v_exp_f32_e32 v81, v81
	v_or_b32_e32 v82, 48, v153
	v_add_f32_e32 v80, 1.0, v80
	v_rcp_f32_e32 v83, v80
	v_add_f32_e32 v80, 1.0, v81
	v_rcp_f32_e32 v84, v80
	v_mad_i64_i32 v[80:81], s[24:25], v82, s49, v[144:145]
	v_mul_f32_e32 v76, v76, v83
	v_mul_f32_e32 v76, v76, v68
	v_mul_f32_e32 v68, v77, v84
	v_mul_f32_e32 v77, 0xbfb8aa3b, v78
	v_exp_f32_e32 v77, v77
	v_mul_f32_e32 v82, 0xbfb8aa3b, v79
	v_exp_f32_e32 v82, v82
	v_mul_f32_e32 v83, v68, v69
	v_add_f32_e32 v68, 1.0, v77
	v_rcp_f32_e32 v68, v68
	v_add_f32_e32 v69, 1.0, v82
	v_mul_f32_e32 v77, 0xbfb8aa3b, v72
	v_rcp_f32_e32 v69, v69
	v_exp_f32_e32 v77, v77
	v_mul_f32_e32 v68, v78, v68
	v_mul_f32_e32 v70, v68, v70
	v_mul_f32_e32 v68, v79, v69
	v_add_f32_e32 v69, 1.0, v77
	v_rcp_f32_e32 v69, v69
	v_mul_f32_e32 v77, 0xbfb8aa3b, v73
	v_mul_f32_e32 v71, v68, v71
	v_exp_f32_e32 v77, v77
	v_mul_f32_e32 v68, v72, v69
	v_mul_f32_e32 v72, v68, v64
	v_mul_f32_e32 v68, 0xbfb8aa3b, v74
	v_exp_f32_e32 v68, v68
	v_mul_f32_e32 v69, 0xbfb8aa3b, v75
	v_exp_f32_e32 v69, v69
	v_add_f32_e32 v64, 1.0, v77
	v_rcp_f32_e32 v64, v64
	v_add_f32_e32 v68, 1.0, v68
	v_rcp_f32_e32 v68, v68
	v_add_f32_e32 v69, 1.0, v69
	v_rcp_f32_e32 v69, v69
	v_mul_f32_e32 v64, v73, v64
	v_mul_f32_e32 v73, v64, v65
	v_mul_f32_e32 v64, v74, v68
	v_mul_f32_e32 v74, v64, v66
	v_mul_f32_e32 v64, v75, v69
	v_mul_f32_e32 v67, v64, v67
	v_lshl_add_u64 v[68:69], v[80:81], 0, v[112:113]
	v_cvt_pk_bf16_f32 v64, v76, v83
	v_cvt_pk_bf16_f32 v65, v70, v71
	v_cvt_pk_bf16_f32 v66, v72, v73
	v_cvt_pk_bf16_f32 v67, v74, v67
	global_store_dwordx4 v[68:69], v[64:67], off nt
	s_nop 1
	v_mul_f32_e32 v64, 0xbfb8aa3b, v60
	v_exp_f32_e32 v64, v64
	v_mul_f32_e32 v65, 0xbfb8aa3b, v61
	v_exp_f32_e32 v65, v65
	v_add_u32_e32 v66, 0x80, v153
	v_add_f32_e32 v64, 1.0, v64
	v_rcp_f32_e32 v67, v64
	v_add_f32_e32 v64, 1.0, v65
	v_rcp_f32_e32 v68, v64
	v_mad_i64_i32 v[64:65], s[24:25], v66, s49, v[144:145]
	v_mul_f32_e32 v60, v60, v67
	v_mul_f32_e32 v60, v60, v52
	v_mul_f32_e32 v52, v61, v68
	v_mul_f32_e32 v61, 0xbfb8aa3b, v62
	v_exp_f32_e32 v61, v61
	v_mul_f32_e32 v66, 0xbfb8aa3b, v63
	v_exp_f32_e32 v66, v66
	v_mul_f32_e32 v67, v52, v53
	v_add_f32_e32 v52, 1.0, v61
	v_rcp_f32_e32 v52, v52
	v_add_f32_e32 v53, 1.0, v66
	v_mul_f32_e32 v61, 0xbfb8aa3b, v56
	v_rcp_f32_e32 v53, v53
	v_exp_f32_e32 v61, v61
	v_mul_f32_e32 v52, v62, v52
	v_mul_f32_e32 v54, v52, v54
	v_mul_f32_e32 v52, v63, v53
	v_add_f32_e32 v53, 1.0, v61
	v_rcp_f32_e32 v53, v53
	v_mul_f32_e32 v61, 0xbfb8aa3b, v57
	v_mul_f32_e32 v55, v52, v55
	v_exp_f32_e32 v61, v61
	v_mul_f32_e32 v52, v56, v53
	v_mul_f32_e32 v56, v52, v48
	v_mul_f32_e32 v52, 0xbfb8aa3b, v58
	v_exp_f32_e32 v52, v52
	v_mul_f32_e32 v53, 0xbfb8aa3b, v59
	v_exp_f32_e32 v53, v53
	v_add_f32_e32 v48, 1.0, v61
	v_rcp_f32_e32 v48, v48
	v_add_f32_e32 v52, 1.0, v52
	v_rcp_f32_e32 v52, v52
	v_add_f32_e32 v53, 1.0, v53
	v_rcp_f32_e32 v53, v53
	v_mul_f32_e32 v48, v57, v48
	v_mul_f32_e32 v57, v48, v49
	v_mul_f32_e32 v48, v58, v52
	v_mul_f32_e32 v58, v48, v50
	v_mul_f32_e32 v48, v59, v53
	v_mul_f32_e32 v51, v48, v51
	v_lshl_add_u64 v[52:53], v[64:65], 0, v[112:113]
	v_cvt_pk_bf16_f32 v48, v60, v67
	v_cvt_pk_bf16_f32 v49, v54, v55
	v_cvt_pk_bf16_f32 v50, v56, v57
	v_cvt_pk_bf16_f32 v51, v58, v51
	global_store_dwordx4 v[52:53], v[48:51], off nt
	s_nop 1
	v_mul_f32_e32 v48, 0xbfb8aa3b, v44
	v_exp_f32_e32 v48, v48
	v_mul_f32_e32 v49, 0xbfb8aa3b, v45
	v_exp_f32_e32 v49, v49
	v_add_u32_e32 v50, 0x90, v153
	v_add_f32_e32 v48, 1.0, v48
	v_rcp_f32_e32 v51, v48
	v_add_f32_e32 v48, 1.0, v49
	v_rcp_f32_e32 v52, v48
	v_mad_i64_i32 v[48:49], s[24:25], v50, s49, v[144:145]
	v_mul_f32_e32 v44, v44, v51
	v_mul_f32_e32 v44, v44, v36
	v_mul_f32_e32 v36, v45, v52
	v_mul_f32_e32 v45, 0xbfb8aa3b, v46
	v_exp_f32_e32 v45, v45
	v_mul_f32_e32 v50, 0xbfb8aa3b, v47
	v_exp_f32_e32 v50, v50
	v_mul_f32_e32 v51, v36, v37
	v_add_f32_e32 v36, 1.0, v45
	v_rcp_f32_e32 v36, v36
	v_add_f32_e32 v37, 1.0, v50
	v_mul_f32_e32 v45, 0xbfb8aa3b, v40
	v_rcp_f32_e32 v37, v37
	v_exp_f32_e32 v45, v45
	v_mul_f32_e32 v36, v46, v36
	v_mul_f32_e32 v38, v36, v38
	v_mul_f32_e32 v36, v47, v37
	v_add_f32_e32 v37, 1.0, v45
	v_rcp_f32_e32 v37, v37
	v_mul_f32_e32 v45, 0xbfb8aa3b, v41
	v_mul_f32_e32 v39, v36, v39
; __device__ __forceinline__ unsigned cvt_pk_bf16(float lo, float hi) { unsigned r; asm volatile("v_cvt_pk_bf16_f32 %0, %1, %2" : "=v"(r) : "v"(lo), "v"(hi)); return r; }
; __device__ __forceinline__ float siluf_(float x) { return x * __builtin_amdgcn_rcpf(1.0f + __expf(-x)); }
; #define PG8_BAR __builtin_amdgcn_s_barrier()
;     __device__ __forceinline__ void operator()(const f32x4 (&acc)[2][2][4][2], const Unit& u, int wr, int wc, int fr, int fq) const {
;         const int row0 = u.pm * BM + wr * 64 + fr, col0 = u.pn * HALF + wc * 32 + 8 * fq;
; #pragma unroll
;         for (int ai = 0; ai < 2; ++ai)
; #pragma unroll
;             for (int m = 0; m < 4; ++m) { bf16_t* rowp = O + (size_t)(row0 + ai * HALF + m * 16) * ldc + col0;
;                 float o[8];
; #pragma unroll
;                 for (int n = 0; n < 2; ++n)
; #pragma unroll
;                     for (int j = 0; j < 4; ++j) { const float g = acc[ai][0][m][n][j], up = acc[ai][1][m][n][j]; o[4 * n + j] = siluf_(g) * up; }
;                 u32x4 w; w.x = cvt_pk_bf16(o[0], o[1]); w.y = cvt_pk_bf16(o[2], o[3]); w.z = cvt_pk_bf16(o[4], o[5]); w.w = cvt_pk_bf16(o[6], o[7]);
;                 *(u32x4*)rowp = w; }
; template <class Epi>
; __device__ __forceinline__ void gemm_phase(LAS unsigned char* lds, const Gemm g, const StaticOrder& S, const Epi& E) {
;     ...
;         if (wr == 0) PG8_BAR;
;         E(acc, cur, wr, wc, fr, fq);
;         if (!has_next) break;
; #pragma unroll
;         for (int a = 0; a < 2; ++a)
; #pragma unroll
;             for (int b = 0; b < 2; ++b)
; #pragma unroll
;                 for (int m = 0; m < 4; ++m)
; #pragma unroll
;                     for (int n = 0; n < 2; ++n) acc[a][b][m][n] = (f32x4){0.f, 0.f, 0.f, 0.f};
;         cur = nxt; cA = nA; cB = nB; ++ui;
;         if (wr == 1) PG8_BAR;
	v_exp_f32_e32 v45, v45
	v_mul_f32_e32 v36, v40, v37
	v_mul_f32_e32 v40, v36, v32
	v_mul_f32_e32 v36, 0xbfb8aa3b, v42
	v_exp_f32_e32 v36, v36
	v_mul_f32_e32 v37, 0xbfb8aa3b, v43
	v_exp_f32_e32 v37, v37
	v_add_f32_e32 v32, 1.0, v45
	v_rcp_f32_e32 v32, v32
	v_add_f32_e32 v36, 1.0, v36
	v_rcp_f32_e32 v36, v36
	v_add_f32_e32 v37, 1.0, v37
	v_rcp_f32_e32 v37, v37
	v_mul_f32_e32 v32, v41, v32
	v_mul_f32_e32 v41, v32, v33
	v_mul_f32_e32 v32, v42, v36
	v_mul_f32_e32 v42, v32, v34
	v_mul_f32_e32 v32, v43, v37
	v_mul_f32_e32 v35, v32, v35
	v_lshl_add_u64 v[36:37], v[48:49], 0, v[112:113]
	v_cvt_pk_bf16_f32 v32, v44, v51
	v_cvt_pk_bf16_f32 v33, v38, v39
	v_cvt_pk_bf16_f32 v34, v40, v41
	v_cvt_pk_bf16_f32 v35, v42, v35
	global_store_dwordx4 v[36:37], v[32:35], off nt
	s_nop 1
	v_mul_f32_e32 v32, 0xbfb8aa3b, v28
	v_exp_f32_e32 v32, v32
	v_mul_f32_e32 v33, 0xbfb8aa3b, v29
	v_exp_f32_e32 v33, v33
	v_add_u32_e32 v34, 0xa0, v153
	v_add_f32_e32 v32, 1.0, v32
	v_rcp_f32_e32 v35, v32
	v_add_f32_e32 v32, 1.0, v33
	v_rcp_f32_e32 v36, v32
	v_mad_i64_i32 v[32:33], s[24:25], v34, s49, v[144:145]
	v_mul_f32_e32 v28, v28, v35
	v_mul_f32_e32 v28, v28, v20
	v_mul_f32_e32 v20, v29, v36
	v_mul_f32_e32 v29, 0xbfb8aa3b, v30
	v_exp_f32_e32 v29, v29
	v_mul_f32_e32 v34, 0xbfb8aa3b, v31
	v_exp_f32_e32 v34, v34
	v_mul_f32_e32 v35, v20, v21
	v_add_f32_e32 v20, 1.0, v29
	v_rcp_f32_e32 v20, v20
	v_add_f32_e32 v21, 1.0, v34
	v_mul_f32_e32 v29, 0xbfb8aa3b, v24
	v_rcp_f32_e32 v21, v21
	v_exp_f32_e32 v29, v29
	v_mul_f32_e32 v20, v30, v20
	v_mul_f32_e32 v22, v20, v22
	v_mul_f32_e32 v20, v31, v21
	v_add_f32_e32 v21, 1.0, v29
	v_rcp_f32_e32 v21, v21
	v_mul_f32_e32 v29, 0xbfb8aa3b, v25
	v_mul_f32_e32 v23, v20, v23
	v_exp_f32_e32 v29, v29
	v_mul_f32_e32 v20, v24, v21
	v_mul_f32_e32 v24, v20, v16
	v_mul_f32_e32 v20, 0xbfb8aa3b, v26
	v_exp_f32_e32 v20, v20
	v_mul_f32_e32 v21, 0xbfb8aa3b, v27
	v_exp_f32_e32 v21, v21
	v_add_f32_e32 v16, 1.0, v29
	v_rcp_f32_e32 v16, v16
	v_add_f32_e32 v20, 1.0, v20
	v_rcp_f32_e32 v20, v20
	v_add_f32_e32 v21, 1.0, v21
	v_rcp_f32_e32 v21, v21
	v_mul_f32_e32 v16, v25, v16
	v_mul_f32_e32 v25, v16, v17
	v_mul_f32_e32 v16, v26, v20
	v_mul_f32_e32 v26, v16, v18
	v_mul_f32_e32 v16, v27, v21
	v_mul_f32_e32 v19, v16, v19
	v_lshl_add_u64 v[20:21], v[32:33], 0, v[112:113]
	v_cvt_pk_bf16_f32 v16, v28, v35
	v_cvt_pk_bf16_f32 v17, v22, v23
	v_cvt_pk_bf16_f32 v18, v24, v25
	v_cvt_pk_bf16_f32 v19, v26, v19
	global_store_dwordx4 v[20:21], v[16:19], off nt
	s_nop 1
	v_mul_f32_e32 v16, 0xbfb8aa3b, v12
	v_exp_f32_e32 v16, v16
	v_mul_f32_e32 v17, 0xbfb8aa3b, v13
	v_exp_f32_e32 v17, v17
	v_add_u32_e32 v18, 0xb0, v153
	v_add_f32_e32 v16, 1.0, v16
	v_rcp_f32_e32 v19, v16
	v_add_f32_e32 v16, 1.0, v17
	v_rcp_f32_e32 v20, v16
	v_mad_i64_i32 v[16:17], s[24:25], v18, s49, v[144:145]
	v_mul_f32_e32 v12, v12, v19
	v_mul_f32_e32 v12, v12, v4
	v_mul_f32_e32 v4, v13, v20
	v_mul_f32_e32 v13, 0xbfb8aa3b, v14
	v_exp_f32_e32 v13, v13
	v_mul_f32_e32 v18, 0xbfb8aa3b, v15
	v_exp_f32_e32 v18, v18
	v_mul_f32_e32 v19, v4, v5
	v_add_f32_e32 v4, 1.0, v13
	v_rcp_f32_e32 v4, v4
	v_add_f32_e32 v5, 1.0, v18
	v_mul_f32_e32 v13, 0xbfb8aa3b, v8
	v_rcp_f32_e32 v5, v5
	v_exp_f32_e32 v13, v13
	v_mul_f32_e32 v4, v14, v4
	v_mul_f32_e32 v6, v4, v6
	v_mul_f32_e32 v4, v15, v5
	v_add_f32_e32 v5, 1.0, v13
	v_rcp_f32_e32 v5, v5
	v_mul_f32_e32 v13, 0xbfb8aa3b, v9
	v_mul_f32_e32 v7, v4, v7
	v_exp_f32_e32 v13, v13
	v_mul_f32_e32 v4, v8, v5
	v_mul_f32_e32 v8, v4, v0
	v_mul_f32_e32 v4, 0xbfb8aa3b, v10
	v_exp_f32_e32 v4, v4
	v_mul_f32_e32 v5, 0xbfb8aa3b, v11
	v_exp_f32_e32 v5, v5
	v_add_f32_e32 v0, 1.0, v13
	v_rcp_f32_e32 v0, v0
	v_add_f32_e32 v4, 1.0, v4
	v_rcp_f32_e32 v4, v4
	v_add_f32_e32 v5, 1.0, v5
	v_rcp_f32_e32 v5, v5
	v_mul_f32_e32 v0, v9, v0
	v_mul_f32_e32 v9, v0, v1
	v_mul_f32_e32 v0, v10, v4
	v_mul_f32_e32 v10, v0, v2
	v_mul_f32_e32 v0, v11, v5
	v_mul_f32_e32 v3, v0, v3
	v_lshl_add_u64 v[4:5], v[16:17], 0, v[112:113]
	v_cvt_pk_bf16_f32 v0, v12, v19
	v_cvt_pk_bf16_f32 v1, v6, v7
	v_cvt_pk_bf16_f32 v2, v8, v9
	v_cvt_pk_bf16_f32 v3, v10, v3
	global_store_dwordx4 v[4:5], v[0:3], off nt
	s_cbranch_vccnz .LBB0_1332
	s_andn2_b64 vcc, exec, s[6:7]
	s_cbranch_vccnz .LBB0_1331
	s_barrier
	s_branch .LBB0_1331

; __device__ __forceinline__ unsigned cvt_pk_bf16(float lo, float hi) { unsigned r; asm volatile("v_cvt_pk_bf16_f32 %0, %1, %2" : "=v"(r) : "v"(lo), "v"(hi)); return r; }
;     __device__ __forceinline__ void operator()(const f32x4 (&acc)[2][2][4][2], const Unit& u, int wr, int wc, int fr, int fq) const {
;         const int row0 = u.pm * BM + wr * 64 + fr, col0 = u.pn * BM + wc * 32 + 8 * fq;
; #pragma unroll
;         for (int ai = 0; ai < 2; ++ai)
; #pragma unroll
;             for (int m = 0; m < 4; ++m) { bf16_t* rowp = O + (size_t)(row0 + ai * HALF + m * 16) * ldc + col0;
; #pragma unroll
;                 for (int bj = 0; bj < 2; ++bj) { const f32x4 v0 = acc[ai][bj][m][0], v1 = acc[ai][bj][m][1];
;                     u32x4 w; w.x = cvt_pk_bf16(v0[0], v0[1]); w.y = cvt_pk_bf16(v0[2], v0[3]); w.z = cvt_pk_bf16(v1[0], v1[1]); w.w = cvt_pk_bf16(v1[2], v1[3]);
;                     *(u32x4*)(rowp + bj * HALF) = w; } }
.LBB0_1575:
	v_lshl_or_b32 v146, s46, 8, v150
	v_lshl_add_u32 v156, s22, 8, v148
	v_ashrrev_i32_e32 v147, 31, v146
	v_mov_b64_e32 v[144:145], s[8:9]
	v_mad_i64_i32 v[154:155], s[24:25], v156, s45, v[144:145]
	v_lshlrev_b64 v[146:147], 1, v[146:147]
	v_lshl_add_u64 v[154:155], v[154:155], 0, v[146:147]
	v_cvt_pk_bf16_f32 v124, v124, v125
	v_cvt_pk_bf16_f32 v125, v126, v127
	v_cvt_pk_bf16_f32 v126, v120, v121
	v_cvt_pk_bf16_f32 v127, v122, v123
	global_store_dwordx4 v[154:155], v[124:127], off nt
	v_cvt_pk_bf16_f32 v112, v112, v113
	v_cvt_pk_bf16_f32 v113, v114, v115
	v_cvt_pk_bf16_f32 v114, v104, v105
	v_or_b32_e32 v104, 16, v156
	v_mad_i64_i32 v[104:105], s[24:25], v104, s45, v[144:145]
	v_cvt_pk_bf16_f32 v115, v106, v107
	global_store_dwordx4 v[154:155], v[112:115], off offset:256 nt
	s_andn2_b64 vcc, exec, s[0:1]
	s_mov_b64 s[0:1], -1
	v_lshl_add_u64 v[112:113], v[104:105], 0, v[146:147]
	v_cvt_pk_bf16_f32 v104, v116, v117
	v_cvt_pk_bf16_f32 v105, v118, v119
	v_cvt_pk_bf16_f32 v106, v108, v109
	v_cvt_pk_bf16_f32 v107, v110, v111
	global_store_dwordx4 v[112:113], v[104:107], off nt
	v_cvt_pk_bf16_f32 v96, v96, v97
	v_cvt_pk_bf16_f32 v97, v98, v99
	v_cvt_pk_bf16_f32 v98, v88, v89
	v_or_b32_e32 v88, 32, v156
	v_mad_i64_i32 v[88:89], s[24:25], v88, s45, v[144:145]
	v_cvt_pk_bf16_f32 v99, v90, v91
	global_store_dwordx4 v[112:113], v[96:99], off offset:256 nt
	s_nop 1
	v_lshl_add_u64 v[96:97], v[88:89], 0, v[146:147]
	v_cvt_pk_bf16_f32 v88, v100, v101
	v_cvt_pk_bf16_f32 v89, v102, v103
	v_cvt_pk_bf16_f32 v90, v92, v93
	v_cvt_pk_bf16_f32 v91, v94, v95
	global_store_dwordx4 v[96:97], v[88:91], off nt
	v_cvt_pk_bf16_f32 v80, v80, v81
	v_cvt_pk_bf16_f32 v81, v82, v83
	v_cvt_pk_bf16_f32 v82, v72, v73
	v_or_b32_e32 v72, 48, v156
	v_mad_i64_i32 v[72:73], s[24:25], v72, s45, v[144:145]
	v_cvt_pk_bf16_f32 v83, v74, v75
	global_store_dwordx4 v[96:97], v[80:83], off offset:256 nt
	s_nop 1
	v_lshl_add_u64 v[80:81], v[72:73], 0, v[146:147]
	v_cvt_pk_bf16_f32 v72, v84, v85
	v_cvt_pk_bf16_f32 v73, v86, v87
	v_cvt_pk_bf16_f32 v74, v76, v77
	v_cvt_pk_bf16_f32 v75, v78, v79
	global_store_dwordx4 v[80:81], v[72:75], off nt
	v_cvt_pk_bf16_f32 v68, v68, v69
	v_cvt_pk_bf16_f32 v69, v70, v71
	v_cvt_pk_bf16_f32 v70, v64, v65
	v_add_u32_e32 v64, 0x80, v156
	v_mad_i64_i32 v[64:65], s[24:25], v64, s45, v[144:145]
	v_lshl_add_u64 v[64:65], v[64:65], 0, v[146:147]
	v_cvt_pk_bf16_f32 v71, v66, v67
	global_store_dwordx4 v[80:81], v[68:71], off offset:256 nt
	v_cvt_pk_bf16_f32 v60, v60, v61
	v_cvt_pk_bf16_f32 v61, v62, v63
	v_cvt_pk_bf16_f32 v62, v56, v57
	v_cvt_pk_bf16_f32 v63, v58, v59
	global_store_dwordx4 v[64:65], v[60:63], off nt
	v_cvt_pk_bf16_f32 v48, v48, v49
	v_cvt_pk_bf16_f32 v49, v50, v51
	v_cvt_pk_bf16_f32 v50, v40, v41
	v_add_u32_e32 v40, 0x90, v156
	v_mad_i64_i32 v[40:41], s[24:25], v40, s45, v[144:145]
	v_cvt_pk_bf16_f32 v51, v42, v43
	global_store_dwordx4 v[64:65], v[48:51], off offset:256 nt
	s_nop 1
	v_lshl_add_u64 v[48:49], v[40:41], 0, v[146:147]
	v_cvt_pk_bf16_f32 v40, v52, v53
	v_cvt_pk_bf16_f32 v41, v54, v55
	v_cvt_pk_bf16_f32 v42, v44, v45
	v_cvt_pk_bf16_f32 v43, v46, v47
	global_store_dwordx4 v[48:49], v[40:43], off nt
	v_cvt_pk_bf16_f32 v32, v32, v33
	v_cvt_pk_bf16_f32 v33, v34, v35
	v_cvt_pk_bf16_f32 v34, v24, v25
	v_add_u32_e32 v24, 0xa0, v156
	v_mad_i64_i32 v[24:25], s[24:25], v24, s45, v[144:145]
	v_cvt_pk_bf16_f32 v35, v26, v27
	global_store_dwordx4 v[48:49], v[32:35], off offset:256 nt
	s_nop 1
	v_lshl_add_u64 v[32:33], v[24:25], 0, v[146:147]
	v_cvt_pk_bf16_f32 v24, v36, v37
	v_cvt_pk_bf16_f32 v25, v38, v39
	v_cvt_pk_bf16_f32 v26, v28, v29
	v_cvt_pk_bf16_f32 v27, v30, v31
	global_store_dwordx4 v[32:33], v[24:27], off nt
	v_cvt_pk_bf16_f32 v16, v16, v17
	v_cvt_pk_bf16_f32 v17, v18, v19
	v_cvt_pk_bf16_f32 v18, v8, v9
	v_add_u32_e32 v8, 0xb0, v156
	v_mad_i64_i32 v[8:9], s[24:25], v8, s45, v[144:145]
	v_cvt_pk_bf16_f32 v19, v10, v11
	global_store_dwordx4 v[32:33], v[16:19], off offset:256 nt
	s_nop 1
	v_lshl_add_u64 v[16:17], v[8:9], 0, v[146:147]
	v_cvt_pk_bf16_f32 v8, v20, v21
	v_cvt_pk_bf16_f32 v9, v22, v23
	v_cvt_pk_bf16_f32 v10, v12, v13
	v_cvt_pk_bf16_f32 v11, v14, v15
	global_store_dwordx4 v[16:17], v[8:11], off nt
	v_cvt_pk_bf16_f32 v4, v4, v5
	v_cvt_pk_bf16_f32 v5, v6, v7
	v_cvt_pk_bf16_f32 v6, v0, v1
	v_cvt_pk_bf16_f32 v7, v2, v3
	global_store_dwordx4 v[16:17], v[4:7], off offset:256 nt
	s_cbranch_vccnz .LBB0_1568
	s_andn2_b64 vcc, exec, s[6:7]
	s_cbranch_vccnz .LBB0_1567
	s_barrier
	s_branch .LBB0_1567

; __device__ __forceinline__ unsigned cvt_pk_bf16(float lo, float hi) { unsigned r; asm volatile("v_cvt_pk_bf16_f32 %0, %1, %2" : "=v"(r) : "v"(lo), "v"(hi)); return r; }
; __device__ __forceinline__ float siluf_(float x) { return x * __builtin_amdgcn_rcpf(1.0f + __expf(-x)); }
;     __device__ __forceinline__ void operator()(const f32x4 (&acc)[2][2][4][2], const Unit& u, int wr, int wc, int fr, int fq) const {
;         const int row0 = u.pm * BM + wr * 64 + fr, col0 = u.pn * HALF + wc * 32 + 8 * fq;
; #pragma unroll
;         for (int ai = 0; ai < 2; ++ai)
; #pragma unroll
;             for (int m = 0; m < 4; ++m) { bf16_t* rowp = O + (size_t)(row0 + ai * HALF + m * 16) * ldc + col0;
;                 float o[8];
; #pragma unroll
;                 for (int n = 0; n < 2; ++n)
; #pragma unroll
;                     for (int j = 0; j < 4; ++j) { const float g = acc[ai][0][m][n][j], up = acc[ai][1][m][n][j]; o[4 * n + j] = siluf_(g) * up; }
;                 u32x4 w; w.x = cvt_pk_bf16(o[0], o[1]); w.y = cvt_pk_bf16(o[2], o[3]); w.z = cvt_pk_bf16(o[4], o[5]); w.w = cvt_pk_bf16(o[6], o[7]);
;                 *(u32x4*)rowp = w; }
.LBB0_2119:
	v_mul_f32_e32 v144, 0xbfb8aa3b, v124
	v_exp_f32_e32 v156, v144
	v_mul_f32_e32 v144, 0xbfb8aa3b, v125
	v_exp_f32_e32 v157, v144
	v_lshl_or_b32 v154, s48, 7, v149
	v_add_f32_e32 v156, 1.0, v156
	v_rcp_f32_e32 v158, v156
	v_add_f32_e32 v156, 1.0, v157
	v_rcp_f32_e32 v159, v156
	v_lshl_add_u32 v153, s22, 8, v147
	v_mul_f32_e32 v124, v124, v158
	v_mul_f32_e32 v116, v124, v116
	v_mul_f32_e32 v124, v125, v159
	v_mul_f32_e32 v125, 0xbfb8aa3b, v126
	v_exp_f32_e32 v125, v125
	v_mul_f32_e32 v158, 0xbfb8aa3b, v127
	v_exp_f32_e32 v158, v158
	v_mul_f32_e32 v117, v124, v117
	v_add_f32_e32 v124, 1.0, v125
	v_rcp_f32_e32 v124, v124
	v_add_f32_e32 v125, 1.0, v158
	v_mul_f32_e32 v158, 0xbfb8aa3b, v120
	v_rcp_f32_e32 v125, v125
	v_exp_f32_e32 v158, v158
	v_mul_f32_e32 v124, v126, v124
	v_mul_f32_e32 v124, v124, v118
	v_mul_f32_e32 v118, v127, v125
	v_add_f32_e32 v125, 1.0, v158
	v_rcp_f32_e32 v125, v125
	v_mul_f32_e32 v126, 0xbfb8aa3b, v121
	v_mul_f32_e32 v127, v118, v119
	v_exp_f32_e32 v126, v126
	v_mul_f32_e32 v118, v120, v125
	v_mul_f32_e32 v120, v118, v112
	v_mul_f32_e32 v118, 0xbfb8aa3b, v122
	v_exp_f32_e32 v118, v118
	v_mul_f32_e32 v119, 0xbfb8aa3b, v123
	v_exp_f32_e32 v119, v119
	v_add_f32_e32 v112, 1.0, v126
	v_rcp_f32_e32 v112, v112
	v_add_f32_e32 v118, 1.0, v118
	v_rcp_f32_e32 v118, v118
	v_add_f32_e32 v119, 1.0, v119
	v_rcp_f32_e32 v119, v119
	v_mul_f32_e32 v112, v121, v112
	v_mul_f32_e32 v121, v112, v113
	v_mul_f32_e32 v112, v122, v118
	v_ashrrev_i32_e32 v155, 31, v154
	v_mov_b64_e32 v[144:145], s[8:9]
	v_mul_f32_e32 v122, v112, v114
	v_mul_f32_e32 v112, v123, v119
	v_mad_i64_i32 v[156:157], s[24:25], v153, s47, v[144:145]
	v_mul_f32_e32 v123, v112, v115
	v_lshlrev_b64 v[112:113], 1, v[154:155]
	v_lshl_add_u64 v[118:119], v[156:157], 0, v[112:113]
	v_cvt_pk_bf16_f32 v114, v116, v117
	v_cvt_pk_bf16_f32 v115, v124, v127
	v_cvt_pk_bf16_f32 v116, v120, v121
	v_cvt_pk_bf16_f32 v117, v122, v123
	global_store_dwordx4 v[118:119], v[114:117], off nt
	s_andn2_b64 vcc, exec, s[0:1]
	s_mov_b64 s[0:1], -1
	v_mul_f32_e32 v114, 0xbfb8aa3b, v108
	v_exp_f32_e32 v114, v114
	v_mul_f32_e32 v115, 0xbfb8aa3b, v109
	v_exp_f32_e32 v115, v115
	v_or_b32_e32 v116, 16, v153
	v_add_f32_e32 v114, 1.0, v114
	v_rcp_f32_e32 v117, v114
	v_add_f32_e32 v114, 1.0, v115
	v_rcp_f32_e32 v118, v114
	v_mad_i64_i32 v[114:115], s[24:25], v116, s47, v[144:145]
	v_mul_f32_e32 v108, v108, v117
	v_mul_f32_e32 v108, v108, v100
	v_mul_f32_e32 v100, v109, v118
	v_mul_f32_e32 v109, 0xbfb8aa3b, v110
	v_exp_f32_e32 v109, v109
	v_mul_f32_e32 v116, 0xbfb8aa3b, v111
	v_exp_f32_e32 v116, v116
	v_mul_f32_e32 v117, v100, v101
	v_add_f32_e32 v100, 1.0, v109
	v_rcp_f32_e32 v100, v100
	v_add_f32_e32 v101, 1.0, v116
	v_mul_f32_e32 v109, 0xbfb8aa3b, v104
	v_rcp_f32_e32 v101, v101
	v_exp_f32_e32 v109, v109
	v_mul_f32_e32 v100, v110, v100
	v_mul_f32_e32 v102, v100, v102
	v_mul_f32_e32 v100, v111, v101
	v_add_f32_e32 v101, 1.0, v109
	v_rcp_f32_e32 v101, v101
	v_mul_f32_e32 v109, 0xbfb8aa3b, v105
	v_mul_f32_e32 v103, v100, v103
	v_exp_f32_e32 v109, v109
	v_mul_f32_e32 v100, v104, v101
	v_mul_f32_e32 v104, v100, v96
	v_mul_f32_e32 v100, 0xbfb8aa3b, v106
	v_exp_f32_e32 v100, v100
	v_mul_f32_e32 v101, 0xbfb8aa3b, v107
	v_exp_f32_e32 v101, v101
	v_add_f32_e32 v96, 1.0, v109
	v_rcp_f32_e32 v96, v96
	v_add_f32_e32 v100, 1.0, v100
	v_rcp_f32_e32 v100, v100
	v_add_f32_e32 v101, 1.0, v101
	v_rcp_f32_e32 v101, v101
	v_mul_f32_e32 v96, v105, v96
	v_mul_f32_e32 v105, v96, v97
	v_mul_f32_e32 v96, v106, v100
	v_mul_f32_e32 v106, v96, v98
	v_mul_f32_e32 v96, v107, v101
	v_mul_f32_e32 v99, v96, v99
	v_lshl_add_u64 v[100:101], v[114:115], 0, v[112:113]
	v_cvt_pk_bf16_f32 v96, v108, v117
	v_cvt_pk_bf16_f32 v97, v102, v103
	v_cvt_pk_bf16_f32 v98, v104, v105
	v_cvt_pk_bf16_f32 v99, v106, v99
	global_store_dwordx4 v[100:101], v[96:99], off nt
	s_nop 1
	v_mul_f32_e32 v96, 0xbfb8aa3b, v92
	v_exp_f32_e32 v96, v96
	v_mul_f32_e32 v97, 0xbfb8aa3b, v93
	v_exp_f32_e32 v97, v97
	v_or_b32_e32 v98, 32, v153
	v_add_f32_e32 v96, 1.0, v96
	v_rcp_f32_e32 v99, v96
	v_add_f32_e32 v96, 1.0, v97
	v_rcp_f32_e32 v100, v96
	v_mad_i64_i32 v[96:97], s[24:25], v98, s47, v[144:145]
	v_mul_f32_e32 v92, v92, v99
	v_mul_f32_e32 v92, v92, v84
	v_mul_f32_e32 v84, v93, v100
	v_mul_f32_e32 v93, 0xbfb8aa3b, v94
	v_exp_f32_e32 v93, v93
	v_mul_f32_e32 v98, 0xbfb8aa3b, v95
	v_exp_f32_e32 v98, v98
	v_mul_f32_e32 v99, v84, v85
	v_add_f32_e32 v84, 1.0, v93
	v_rcp_f32_e32 v84, v84
	v_add_f32_e32 v85, 1.0, v98
	v_mul_f32_e32 v93, 0xbfb8aa3b, v88
	v_rcp_f32_e32 v85, v85
	v_exp_f32_e32 v93, v93
	v_mul_f32_e32 v84, v94, v84
	v_mul_f32_e32 v86, v84, v86
	v_mul_f32_e32 v84, v95, v85
	v_add_f32_e32 v85, 1.0, v93
	v_rcp_f32_e32 v85, v85
	v_mul_f32_e32 v93, 0xbfb8aa3b, v89
	v_mul_f32_e32 v87, v84, v87
	v_exp_f32_e32 v93, v93
	v_mul_f32_e32 v84, v88, v85
	v_mul_f32_e32 v88, v84, v80
	v_mul_f32_e32 v84, 0xbfb8aa3b, v90
	v_exp_f32_e32 v84, v84
	v_mul_f32_e32 v85, 0xbfb8aa3b, v91
	v_exp_f32_e32 v85, v85
	v_add_f32_e32 v80, 1.0, v93
	v_rcp_f32_e32 v80, v80
	v_add_f32_e32 v84, 1.0, v84
	v_rcp_f32_e32 v84, v84
	v_add_f32_e32 v85, 1.0, v85
	v_rcp_f32_e32 v85, v85
	v_mul_f32_e32 v80, v89, v80
	v_mul_f32_e32 v89, v80, v81
	v_mul_f32_e32 v80, v90, v84
	v_mul_f32_e32 v90, v80, v82
	v_mul_f32_e32 v80, v91, v85
	v_mul_f32_e32 v83, v80, v83
	v_lshl_add_u64 v[84:85], v[96:97], 0, v[112:113]
	v_cvt_pk_bf16_f32 v80, v92, v99
	v_cvt_pk_bf16_f32 v81, v86, v87
	v_cvt_pk_bf16_f32 v82, v88, v89
	v_cvt_pk_bf16_f32 v83, v90, v83
	global_store_dwordx4 v[84:85], v[80:83], off nt
	s_nop 1
	v_mul_f32_e32 v80, 0xbfb8aa3b, v76
	v_exp_f32_e32 v80, v80
	v_mul_f32_e32 v81, 0xbfb8aa3b, v77
; __device__ __forceinline__ unsigned cvt_pk_bf16(float lo, float hi) { unsigned r; asm volatile("v_cvt_pk_bf16_f32 %0, %1, %2" : "=v"(r) : "v"(lo), "v"(hi)); return r; }
; __device__ __forceinline__ float siluf_(float x) { return x * __builtin_amdgcn_rcpf(1.0f + __expf(-x)); }
;     __device__ __forceinline__ void operator()(const f32x4 (&acc)[2][2][4][2], const Unit& u, int wr, int wc, int fr, int fq) const {
;         const int row0 = u.pm * BM + wr * 64 + fr, col0 = u.pn * HALF + wc * 32 + 8 * fq;
; #pragma unroll
;         for (int ai = 0; ai < 2; ++ai)
; #pragma unroll
;             for (int m = 0; m < 4; ++m) { bf16_t* rowp = O + (size_t)(row0 + ai * HALF + m * 16) * ldc + col0;
;                 float o[8];
; #pragma unroll
;                 for (int n = 0; n < 2; ++n)
; #pragma unroll
;                     for (int j = 0; j < 4; ++j) { const float g = acc[ai][0][m][n][j], up = acc[ai][1][m][n][j]; o[4 * n + j] = siluf_(g) * up; }
;                 u32x4 w; w.x = cvt_pk_bf16(o[0], o[1]); w.y = cvt_pk_bf16(o[2], o[3]); w.z = cvt_pk_bf16(o[4], o[5]); w.w = cvt_pk_bf16(o[6], o[7]);
;                 *(u32x4*)rowp = w; }
	v_exp_f32_e32 v81, v81
	v_or_b32_e32 v82, 48, v153
	v_add_f32_e32 v80, 1.0, v80
	v_rcp_f32_e32 v83, v80
	v_add_f32_e32 v80, 1.0, v81
	v_rcp_f32_e32 v84, v80
	v_mad_i64_i32 v[80:81], s[24:25], v82, s47, v[144:145]
	v_mul_f32_e32 v76, v76, v83
	v_mul_f32_e32 v76, v76, v68
	v_mul_f32_e32 v68, v77, v84
	v_mul_f32_e32 v77, 0xbfb8aa3b, v78
	v_exp_f32_e32 v77, v77
	v_mul_f32_e32 v82, 0xbfb8aa3b, v79
	v_exp_f32_e32 v82, v82
	v_mul_f32_e32 v83, v68, v69
	v_add_f32_e32 v68, 1.0, v77
	v_rcp_f32_e32 v68, v68
	v_add_f32_e32 v69, 1.0, v82
	v_mul_f32_e32 v77, 0xbfb8aa3b, v72
	v_rcp_f32_e32 v69, v69
	v_exp_f32_e32 v77, v77
	v_mul_f32_e32 v68, v78, v68
	v_mul_f32_e32 v70, v68, v70
	v_mul_f32_e32 v68, v79, v69
	v_add_f32_e32 v69, 1.0, v77
	v_rcp_f32_e32 v69, v69
	v_mul_f32_e32 v77, 0xbfb8aa3b, v73
	v_mul_f32_e32 v71, v68, v71
	v_exp_f32_e32 v77, v77
	v_mul_f32_e32 v68, v72, v69
	v_mul_f32_e32 v72, v68, v64
	v_mul_f32_e32 v68, 0xbfb8aa3b, v74
	v_exp_f32_e32 v68, v68
	v_mul_f32_e32 v69, 0xbfb8aa3b, v75
	v_exp_f32_e32 v69, v69
	v_add_f32_e32 v64, 1.0, v77
	v_rcp_f32_e32 v64, v64
	v_add_f32_e32 v68, 1.0, v68
	v_rcp_f32_e32 v68, v68
	v_add_f32_e32 v69, 1.0, v69
	v_rcp_f32_e32 v69, v69
	v_mul_f32_e32 v64, v73, v64
	v_mul_f32_e32 v73, v64, v65
	v_mul_f32_e32 v64, v74, v68
	v_mul_f32_e32 v74, v64, v66
	v_mul_f32_e32 v64, v75, v69
	v_mul_f32_e32 v67, v64, v67
	v_lshl_add_u64 v[68:69], v[80:81], 0, v[112:113]
	v_cvt_pk_bf16_f32 v64, v76, v83
	v_cvt_pk_bf16_f32 v65, v70, v71
	v_cvt_pk_bf16_f32 v66, v72, v73
	v_cvt_pk_bf16_f32 v67, v74, v67
	global_store_dwordx4 v[68:69], v[64:67], off nt
	s_nop 1
	v_mul_f32_e32 v64, 0xbfb8aa3b, v60
	v_exp_f32_e32 v64, v64
	v_mul_f32_e32 v65, 0xbfb8aa3b, v61
	v_exp_f32_e32 v65, v65
	v_add_u32_e32 v66, 0x80, v153
	v_add_f32_e32 v64, 1.0, v64
	v_rcp_f32_e32 v67, v64
	v_add_f32_e32 v64, 1.0, v65
	v_rcp_f32_e32 v68, v64
	v_mad_i64_i32 v[64:65], s[24:25], v66, s47, v[144:145]
	v_mul_f32_e32 v60, v60, v67
	v_mul_f32_e32 v60, v60, v52
	v_mul_f32_e32 v52, v61, v68
	v_mul_f32_e32 v61, 0xbfb8aa3b, v62
	v_exp_f32_e32 v61, v61
	v_mul_f32_e32 v66, 0xbfb8aa3b, v63
	v_exp_f32_e32 v66, v66
	v_mul_f32_e32 v67, v52, v53
	v_add_f32_e32 v52, 1.0, v61
	v_rcp_f32_e32 v52, v52
	v_add_f32_e32 v53, 1.0, v66
	v_mul_f32_e32 v61, 0xbfb8aa3b, v56
	v_rcp_f32_e32 v53, v53
	v_exp_f32_e32 v61, v61
	v_mul_f32_e32 v52, v62, v52
	v_mul_f32_e32 v54, v52, v54
	v_mul_f32_e32 v52, v63, v53
	v_add_f32_e32 v53, 1.0, v61
	v_rcp_f32_e32 v53, v53
	v_mul_f32_e32 v61, 0xbfb8aa3b, v57
	v_mul_f32_e32 v55, v52, v55
	v_exp_f32_e32 v61, v61
	v_mul_f32_e32 v52, v56, v53
	v_mul_f32_e32 v56, v52, v48
	v_mul_f32_e32 v52, 0xbfb8aa3b, v58
	v_exp_f32_e32 v52, v52
	v_mul_f32_e32 v53, 0xbfb8aa3b, v59
	v_exp_f32_e32 v53, v53
	v_add_f32_e32 v48, 1.0, v61
	v_rcp_f32_e32 v48, v48
	v_add_f32_e32 v52, 1.0, v52
	v_rcp_f32_e32 v52, v52
	v_add_f32_e32 v53, 1.0, v53
	v_rcp_f32_e32 v53, v53
	v_mul_f32_e32 v48, v57, v48
	v_mul_f32_e32 v57, v48, v49
	v_mul_f32_e32 v48, v58, v52
	v_mul_f32_e32 v58, v48, v50
	v_mul_f32_e32 v48, v59, v53
	v_mul_f32_e32 v51, v48, v51
	v_lshl_add_u64 v[52:53], v[64:65], 0, v[112:113]
	v_cvt_pk_bf16_f32 v48, v60, v67
	v_cvt_pk_bf16_f32 v49, v54, v55
	v_cvt_pk_bf16_f32 v50, v56, v57
	v_cvt_pk_bf16_f32 v51, v58, v51
	global_store_dwordx4 v[52:53], v[48:51], off nt
	s_nop 1
	v_mul_f32_e32 v48, 0xbfb8aa3b, v44
	v_exp_f32_e32 v48, v48
	v_mul_f32_e32 v49, 0xbfb8aa3b, v45
	v_exp_f32_e32 v49, v49
	v_add_u32_e32 v50, 0x90, v153
	v_add_f32_e32 v48, 1.0, v48
	v_rcp_f32_e32 v51, v48
	v_add_f32_e32 v48, 1.0, v49
	v_rcp_f32_e32 v52, v48
	v_mad_i64_i32 v[48:49], s[24:25], v50, s47, v[144:145]
	v_mul_f32_e32 v44, v44, v51
	v_mul_f32_e32 v44, v44, v36
	v_mul_f32_e32 v36, v45, v52
	v_mul_f32_e32 v45, 0xbfb8aa3b, v46
	v_exp_f32_e32 v45, v45
	v_mul_f32_e32 v50, 0xbfb8aa3b, v47
	v_exp_f32_e32 v50, v50
	v_mul_f32_e32 v51, v36, v37
	v_add_f32_e32 v36, 1.0, v45
	v_rcp_f32_e32 v36, v36
	v_add_f32_e32 v37, 1.0, v50
	v_mul_f32_e32 v45, 0xbfb8aa3b, v40
	v_rcp_f32_e32 v37, v37
	v_exp_f32_e32 v45, v45
	v_mul_f32_e32 v36, v46, v36
	v_mul_f32_e32 v38, v36, v38
	v_mul_f32_e32 v36, v47, v37
	v_add_f32_e32 v37, 1.0, v45
	v_rcp_f32_e32 v37, v37
	v_mul_f32_e32 v45, 0xbfb8aa3b, v41
	v_mul_f32_e32 v39, v36, v39
; __device__ __forceinline__ unsigned cvt_pk_bf16(float lo, float hi) { unsigned r; asm volatile("v_cvt_pk_bf16_f32 %0, %1, %2" : "=v"(r) : "v"(lo), "v"(hi)); return r; }
; __device__ __forceinline__ float siluf_(float x) { return x * __builtin_amdgcn_rcpf(1.0f + __expf(-x)); }
; #define PG8_BAR __builtin_amdgcn_s_barrier()
;     __device__ __forceinline__ void operator()(const f32x4 (&acc)[2][2][4][2], const Unit& u, int wr, int wc, int fr, int fq) const {
;         const int row0 = u.pm * BM + wr * 64 + fr, col0 = u.pn * HALF + wc * 32 + 8 * fq;
; #pragma unroll
;         for (int ai = 0; ai < 2; ++ai)
; #pragma unroll
;             for (int m = 0; m < 4; ++m) { bf16_t* rowp = O + (size_t)(row0 + ai * HALF + m * 16) * ldc + col0;
;                 float o[8];
; #pragma unroll
;                 for (int n = 0; n < 2; ++n)
; #pragma unroll
;                     for (int j = 0; j < 4; ++j) { const float g = acc[ai][0][m][n][j], up = acc[ai][1][m][n][j]; o[4 * n + j] = siluf_(g) * up; }
;                 u32x4 w; w.x = cvt_pk_bf16(o[0], o[1]); w.y = cvt_pk_bf16(o[2], o[3]); w.z = cvt_pk_bf16(o[4], o[5]); w.w = cvt_pk_bf16(o[6], o[7]);
;                 *(u32x4*)rowp = w; }
; template <class Epi>
; __device__ __forceinline__ void gemm_phase(LAS unsigned char* lds, const Gemm g, const StaticOrder& S, const Epi& E) {
;     ...
;         if (wr == 0) PG8_BAR;
;         E(acc, cur, wr, wc, fr, fq);
;         if (!has_next) break;
; #pragma unroll
;         for (int a = 0; a < 2; ++a)
; #pragma unroll
;             for (int b = 0; b < 2; ++b)
; #pragma unroll
;                 for (int m = 0; m < 4; ++m)
; #pragma unroll
;                     for (int n = 0; n < 2; ++n) acc[a][b][m][n] = (f32x4){0.f, 0.f, 0.f, 0.f};
;         cur = nxt; cA = nA; cB = nB; ++ui;
;         if (wr == 1) PG8_BAR;
	v_exp_f32_e32 v45, v45
	v_mul_f32_e32 v36, v40, v37
	v_mul_f32_e32 v40, v36, v32
	v_mul_f32_e32 v36, 0xbfb8aa3b, v42
	v_exp_f32_e32 v36, v36
	v_mul_f32_e32 v37, 0xbfb8aa3b, v43
	v_exp_f32_e32 v37, v37
	v_add_f32_e32 v32, 1.0, v45
	v_rcp_f32_e32 v32, v32
	v_add_f32_e32 v36, 1.0, v36
	v_rcp_f32_e32 v36, v36
	v_add_f32_e32 v37, 1.0, v37
	v_rcp_f32_e32 v37, v37
	v_mul_f32_e32 v32, v41, v32
	v_mul_f32_e32 v41, v32, v33
	v_mul_f32_e32 v32, v42, v36
	v_mul_f32_e32 v42, v32, v34
	v_mul_f32_e32 v32, v43, v37
	v_mul_f32_e32 v35, v32, v35
	v_lshl_add_u64 v[36:37], v[48:49], 0, v[112:113]
	v_cvt_pk_bf16_f32 v32, v44, v51
	v_cvt_pk_bf16_f32 v33, v38, v39
	v_cvt_pk_bf16_f32 v34, v40, v41
	v_cvt_pk_bf16_f32 v35, v42, v35
	global_store_dwordx4 v[36:37], v[32:35], off nt
	s_nop 1
	v_mul_f32_e32 v32, 0xbfb8aa3b, v28
	v_exp_f32_e32 v32, v32
	v_mul_f32_e32 v33, 0xbfb8aa3b, v29
	v_exp_f32_e32 v33, v33
	v_add_u32_e32 v34, 0xa0, v153
	v_add_f32_e32 v32, 1.0, v32
	v_rcp_f32_e32 v35, v32
	v_add_f32_e32 v32, 1.0, v33
	v_rcp_f32_e32 v36, v32
	v_mad_i64_i32 v[32:33], s[24:25], v34, s47, v[144:145]
	v_mul_f32_e32 v28, v28, v35
	v_mul_f32_e32 v28, v28, v20
	v_mul_f32_e32 v20, v29, v36
	v_mul_f32_e32 v29, 0xbfb8aa3b, v30
	v_exp_f32_e32 v29, v29
	v_mul_f32_e32 v34, 0xbfb8aa3b, v31
	v_exp_f32_e32 v34, v34
	v_mul_f32_e32 v35, v20, v21
	v_add_f32_e32 v20, 1.0, v29
	v_rcp_f32_e32 v20, v20
	v_add_f32_e32 v21, 1.0, v34
	v_mul_f32_e32 v29, 0xbfb8aa3b, v24
	v_rcp_f32_e32 v21, v21
	v_exp_f32_e32 v29, v29
	v_mul_f32_e32 v20, v30, v20
	v_mul_f32_e32 v22, v20, v22
	v_mul_f32_e32 v20, v31, v21
	v_add_f32_e32 v21, 1.0, v29
	v_rcp_f32_e32 v21, v21
	v_mul_f32_e32 v29, 0xbfb8aa3b, v25
	v_mul_f32_e32 v23, v20, v23
	v_exp_f32_e32 v29, v29
	v_mul_f32_e32 v20, v24, v21
	v_mul_f32_e32 v24, v20, v16
	v_mul_f32_e32 v20, 0xbfb8aa3b, v26
	v_exp_f32_e32 v20, v20
	v_mul_f32_e32 v21, 0xbfb8aa3b, v27
	v_exp_f32_e32 v21, v21
	v_add_f32_e32 v16, 1.0, v29
	v_rcp_f32_e32 v16, v16
	v_add_f32_e32 v20, 1.0, v20
	v_rcp_f32_e32 v20, v20
	v_add_f32_e32 v21, 1.0, v21
	v_rcp_f32_e32 v21, v21
	v_mul_f32_e32 v16, v25, v16
	v_mul_f32_e32 v25, v16, v17
	v_mul_f32_e32 v16, v26, v20
	v_mul_f32_e32 v26, v16, v18
	v_mul_f32_e32 v16, v27, v21
	v_mul_f32_e32 v19, v16, v19
	v_lshl_add_u64 v[20:21], v[32:33], 0, v[112:113]
	v_cvt_pk_bf16_f32 v16, v28, v35
	v_cvt_pk_bf16_f32 v17, v22, v23
	v_cvt_pk_bf16_f32 v18, v24, v25
	v_cvt_pk_bf16_f32 v19, v26, v19
	global_store_dwordx4 v[20:21], v[16:19], off nt
	s_nop 1
	v_mul_f32_e32 v16, 0xbfb8aa3b, v12
	v_exp_f32_e32 v16, v16
	v_mul_f32_e32 v17, 0xbfb8aa3b, v13
	v_exp_f32_e32 v17, v17
	v_add_u32_e32 v18, 0xb0, v153
	v_add_f32_e32 v16, 1.0, v16
	v_rcp_f32_e32 v19, v16
	v_add_f32_e32 v16, 1.0, v17
	v_rcp_f32_e32 v20, v16
	v_mad_i64_i32 v[16:17], s[24:25], v18, s47, v[144:145]
	v_mul_f32_e32 v12, v12, v19
	v_mul_f32_e32 v12, v12, v4
	v_mul_f32_e32 v4, v13, v20
	v_mul_f32_e32 v13, 0xbfb8aa3b, v14
	v_exp_f32_e32 v13, v13
	v_mul_f32_e32 v18, 0xbfb8aa3b, v15
	v_exp_f32_e32 v18, v18
	v_mul_f32_e32 v19, v4, v5
	v_add_f32_e32 v4, 1.0, v13
	v_rcp_f32_e32 v4, v4
	v_add_f32_e32 v5, 1.0, v18
	v_mul_f32_e32 v13, 0xbfb8aa3b, v8
	v_rcp_f32_e32 v5, v5
	v_exp_f32_e32 v13, v13
	v_mul_f32_e32 v4, v14, v4
	v_mul_f32_e32 v6, v4, v6
	v_mul_f32_e32 v4, v15, v5
	v_add_f32_e32 v5, 1.0, v13
	v_rcp_f32_e32 v5, v5
	v_mul_f32_e32 v13, 0xbfb8aa3b, v9
	v_mul_f32_e32 v7, v4, v7
	v_exp_f32_e32 v13, v13
	v_mul_f32_e32 v4, v8, v5
	v_mul_f32_e32 v8, v4, v0
	v_mul_f32_e32 v4, 0xbfb8aa3b, v10
	v_exp_f32_e32 v4, v4
	v_mul_f32_e32 v5, 0xbfb8aa3b, v11
	v_exp_f32_e32 v5, v5
	v_add_f32_e32 v0, 1.0, v13
	v_rcp_f32_e32 v0, v0
	v_add_f32_e32 v4, 1.0, v4
	v_rcp_f32_e32 v4, v4
	v_add_f32_e32 v5, 1.0, v5
	v_rcp_f32_e32 v5, v5
	v_mul_f32_e32 v0, v9, v0
	v_mul_f32_e32 v9, v0, v1
	v_mul_f32_e32 v0, v10, v4
	v_mul_f32_e32 v10, v0, v2
	v_mul_f32_e32 v0, v11, v5
	v_mul_f32_e32 v3, v0, v3
	v_lshl_add_u64 v[4:5], v[16:17], 0, v[112:113]
	v_cvt_pk_bf16_f32 v0, v12, v19
	v_cvt_pk_bf16_f32 v1, v6, v7
	v_cvt_pk_bf16_f32 v2, v8, v9
	v_cvt_pk_bf16_f32 v3, v10, v3
	global_store_dwordx4 v[4:5], v[0:3], off nt
	s_cbranch_vccnz .LBB0_2112
	s_andn2_b64 vcc, exec, s[6:7]
	s_cbranch_vccnz .LBB0_2111
	s_barrier
	s_branch .LBB0_2111
